# v59 plus hand-written SwiGLU GEMM epilogue: packed f32 mul/add on adjacent accumulator pairs, same per-element op order (bit-identical), 57 percent fewer non-transcendental VALU ops
# speedup vs baseline: 1.0254x; 1.0012x over previous
.LBB0_673:
	s_waitcnt lgkmcnt(0)
	s_lshl_b32 s0, s65, 10
	s_and_b32 s0, s0, 0x400
	s_add_i32 s0, s0, 0x20000
	s_and_b64 vcc, exec, s[6:7]
	v_lshl_add_u32 v1, s50, 8, v151
	v_lshl_add_u32 v2, v154, 2, s0
	ds_read_b32 v160, v2
	v_bitop3_b32 v3, v1, s61, 16 bitop3:0xc8
	v_lshl_add_u32 v3, v3, 2, s0
	ds_read_b32 v162, v3
	v_bitop3_b32 v2, v1, s62, 32 bitop3:0xc8
	v_lshl_add_u32 v2, v2, 2, s0
	ds_read_b32 v164, v2
	v_bitop3_b32 v3, v1, s63, 48 bitop3:0xc8
	v_lshl_add_u32 v3, v3, 2, s0
	ds_read_b32 v166, v3
	v_add_u32_e32 v2, 0x80, v1
	v_and_b32_e32 v2, 0xcf, v2
	v_lshl_add_u32 v2, v2, 2, s0
	ds_read_b32 v168, v2
	v_add_u32_e32 v3, 0x90, v1
	v_and_b32_e32 v3, 0xdf, v3
	v_lshl_add_u32 v3, v3, 2, s0
	ds_read_b32 v170, v3
	v_add_u32_e32 v2, 0xa0, v1
	v_and_b32_e32 v2, 0xef, v2
	v_lshl_add_u32 v2, v2, 2, s0
	ds_read_b32 v172, v2
	v_add_u32_e32 v3, 0xb0, v1
	v_and_b32_e32 v3, 0xff, v3
	v_lshl_add_u32 v3, v3, 2, s0
	ds_read_b32 v174, v3
	v_lshl_add_u32 v158, s52, 7, v153
	v_ashrrev_i32_e32 v159, 31, v158
	v_mov_b64_e32 v[176:177], s[28:29]
	v_mov_b32_e32 v178, 0xbfb8aa3b
	v_mov_b32_e32 v180, 1.0
	v_lshl_add_u64 v[176:177], v[158:159], 1, v[176:177]
	s_waitcnt lgkmcnt(0)
	v_pk_mul_f32 v[120:121], v[120:121], v[160:161] op_sel_hi:[1,0]
	v_pk_mul_f32 v[122:123], v[122:123], v[160:161] op_sel_hi:[1,0]
	v_pk_mul_f32 v[116:117], v[116:117], v[160:161] op_sel_hi:[1,0]
	v_pk_mul_f32 v[118:119], v[118:119], v[160:161] op_sel_hi:[1,0]
	v_pk_mul_f32 v[128:129], v[128:129], v[160:161] op_sel_hi:[1,0]
	v_pk_mul_f32 v[130:131], v[130:131], v[160:161] op_sel_hi:[1,0]
	v_pk_mul_f32 v[124:125], v[124:125], v[160:161] op_sel_hi:[1,0]
	v_pk_mul_f32 v[126:127], v[126:127], v[160:161] op_sel_hi:[1,0]
	v_pk_mul_f32 v[182:183], v[120:121], v[178:179] op_sel_hi:[1,0]
	v_pk_mul_f32 v[184:185], v[122:123], v[178:179] op_sel_hi:[1,0]
	v_pk_mul_f32 v[186:187], v[116:117], v[178:179] op_sel_hi:[1,0]
	v_pk_mul_f32 v[188:189], v[118:119], v[178:179] op_sel_hi:[1,0]
	v_exp_f32_e32 v182, v182
	v_exp_f32_e32 v183, v183
	v_exp_f32_e32 v184, v184
	v_exp_f32_e32 v185, v185
	v_exp_f32_e32 v186, v186
	v_exp_f32_e32 v187, v187
	v_exp_f32_e32 v188, v188
	v_exp_f32_e32 v189, v189
	v_pk_add_f32 v[182:183], v[182:183], v[180:181] op_sel_hi:[1,0]
	v_pk_add_f32 v[184:185], v[184:185], v[180:181] op_sel_hi:[1,0]
	v_pk_add_f32 v[186:187], v[186:187], v[180:181] op_sel_hi:[1,0]
	v_pk_add_f32 v[188:189], v[188:189], v[180:181] op_sel_hi:[1,0]
	v_rcp_f32_e32 v182, v182
	v_rcp_f32_e32 v183, v183
	v_rcp_f32_e32 v184, v184
	v_rcp_f32_e32 v185, v185
	v_rcp_f32_e32 v186, v186
	v_rcp_f32_e32 v187, v187
	v_rcp_f32_e32 v188, v188
	v_rcp_f32_e32 v189, v189
	v_pk_mul_f32 v[120:121], v[120:121], v[182:183]
	v_pk_mul_f32 v[122:123], v[122:123], v[184:185]
	v_pk_mul_f32 v[116:117], v[116:117], v[186:187]
	v_pk_mul_f32 v[118:119], v[118:119], v[188:189]
	v_pk_mul_f32 v[128:129], v[128:129], v[120:121]
	v_pk_mul_f32 v[130:131], v[130:131], v[122:123]
	v_pk_mul_f32 v[124:125], v[124:125], v[116:117]
	v_pk_mul_f32 v[126:127], v[126:127], v[118:119]
	v_cvt_pk_bf16_f32 v198, v128, v129
	v_cvt_pk_bf16_f32 v199, v130, v131
	v_cvt_pk_bf16_f32 v200, v124, v125
	v_cvt_pk_bf16_f32 v201, v126, v127
	v_mad_i64_i32 v[214:215], s[4:5], v1, s60, v[176:177]
	global_store_dwordx4 v[214:215], v[198:201], off
	v_pk_mul_f32 v[104:105], v[104:105], v[162:163] op_sel_hi:[1,0]
	v_pk_mul_f32 v[106:107], v[106:107], v[162:163] op_sel_hi:[1,0]
	v_pk_mul_f32 v[100:101], v[100:101], v[162:163] op_sel_hi:[1,0]
	v_pk_mul_f32 v[102:103], v[102:103], v[162:163] op_sel_hi:[1,0]
	v_pk_mul_f32 v[112:113], v[112:113], v[162:163] op_sel_hi:[1,0]
	v_pk_mul_f32 v[114:115], v[114:115], v[162:163] op_sel_hi:[1,0]
	v_pk_mul_f32 v[108:109], v[108:109], v[162:163] op_sel_hi:[1,0]
	v_pk_mul_f32 v[110:111], v[110:111], v[162:163] op_sel_hi:[1,0]
	v_pk_mul_f32 v[190:191], v[104:105], v[178:179] op_sel_hi:[1,0]
	v_pk_mul_f32 v[192:193], v[106:107], v[178:179] op_sel_hi:[1,0]
	v_pk_mul_f32 v[194:195], v[100:101], v[178:179] op_sel_hi:[1,0]
	v_pk_mul_f32 v[196:197], v[102:103], v[178:179] op_sel_hi:[1,0]
	v_exp_f32_e32 v190, v190
	v_exp_f32_e32 v191, v191
	v_exp_f32_e32 v192, v192
	v_exp_f32_e32 v193, v193
	v_exp_f32_e32 v194, v194
	v_exp_f32_e32 v195, v195
	v_exp_f32_e32 v196, v196
	v_exp_f32_e32 v197, v197
	v_pk_add_f32 v[190:191], v[190:191], v[180:181] op_sel_hi:[1,0]
	v_pk_add_f32 v[192:193], v[192:193], v[180:181] op_sel_hi:[1,0]
	v_pk_add_f32 v[194:195], v[194:195], v[180:181] op_sel_hi:[1,0]
	v_pk_add_f32 v[196:197], v[196:197], v[180:181] op_sel_hi:[1,0]
	v_rcp_f32_e32 v190, v190
	v_rcp_f32_e32 v191, v191
	v_rcp_f32_e32 v192, v192
	v_rcp_f32_e32 v193, v193
	v_rcp_f32_e32 v194, v194
	v_rcp_f32_e32 v195, v195
	v_rcp_f32_e32 v196, v196
	v_rcp_f32_e32 v197, v197
	v_pk_mul_f32 v[104:105], v[104:105], v[190:191]
	v_pk_mul_f32 v[106:107], v[106:107], v[192:193]
	v_pk_mul_f32 v[100:101], v[100:101], v[194:195]
	v_pk_mul_f32 v[102:103], v[102:103], v[196:197]
	v_pk_mul_f32 v[112:113], v[112:113], v[104:105]
	v_pk_mul_f32 v[114:115], v[114:115], v[106:107]
	v_pk_mul_f32 v[108:109], v[108:109], v[100:101]
	v_pk_mul_f32 v[110:111], v[110:111], v[102:103]
	v_or_b32_e32 v2, 0x10, v1
	v_cvt_pk_bf16_f32 v202, v112, v113
	v_cvt_pk_bf16_f32 v203, v114, v115
	v_cvt_pk_bf16_f32 v204, v108, v109
	v_cvt_pk_bf16_f32 v205, v110, v111
	v_mad_i64_i32 v[216:217], s[4:5], v2, s60, v[176:177]
	global_store_dwordx4 v[216:217], v[202:205], off
	v_pk_mul_f32 v[88:89], v[88:89], v[164:165] op_sel_hi:[1,0]
	v_pk_mul_f32 v[90:91], v[90:91], v[164:165] op_sel_hi:[1,0]
	v_pk_mul_f32 v[84:85], v[84:85], v[164:165] op_sel_hi:[1,0]
	v_pk_mul_f32 v[86:87], v[86:87], v[164:165] op_sel_hi:[1,0]
	v_pk_mul_f32 v[96:97], v[96:97], v[164:165] op_sel_hi:[1,0]
	v_pk_mul_f32 v[98:99], v[98:99], v[164:165] op_sel_hi:[1,0]
	v_pk_mul_f32 v[92:93], v[92:93], v[164:165] op_sel_hi:[1,0]
	v_pk_mul_f32 v[94:95], v[94:95], v[164:165] op_sel_hi:[1,0]
	v_pk_mul_f32 v[182:183], v[88:89], v[178:179] op_sel_hi:[1,0]
	v_pk_mul_f32 v[184:185], v[90:91], v[178:179] op_sel_hi:[1,0]
	v_pk_mul_f32 v[186:187], v[84:85], v[178:179] op_sel_hi:[1,0]
	v_pk_mul_f32 v[188:189], v[86:87], v[178:179] op_sel_hi:[1,0]
	v_exp_f32_e32 v182, v182
	v_exp_f32_e32 v183, v183
	v_exp_f32_e32 v184, v184
	v_exp_f32_e32 v185, v185
	v_exp_f32_e32 v186, v186
	v_exp_f32_e32 v187, v187
	v_exp_f32_e32 v188, v188
	v_exp_f32_e32 v189, v189
	v_pk_add_f32 v[182:183], v[182:183], v[180:181] op_sel_hi:[1,0]
	v_pk_add_f32 v[184:185], v[184:185], v[180:181] op_sel_hi:[1,0]
	v_pk_add_f32 v[186:187], v[186:187], v[180:181] op_sel_hi:[1,0]
	v_pk_add_f32 v[188:189], v[188:189], v[180:181] op_sel_hi:[1,0]
	v_rcp_f32_e32 v182, v182
	v_rcp_f32_e32 v183, v183
	v_rcp_f32_e32 v184, v184
	v_rcp_f32_e32 v185, v185
	v_rcp_f32_e32 v186, v186
	v_rcp_f32_e32 v187, v187
	v_rcp_f32_e32 v188, v188
	v_rcp_f32_e32 v189, v189
	v_pk_mul_f32 v[88:89], v[88:89], v[182:183]
	v_pk_mul_f32 v[90:91], v[90:91], v[184:185]
	v_pk_mul_f32 v[84:85], v[84:85], v[186:187]
	v_pk_mul_f32 v[86:87], v[86:87], v[188:189]
	v_pk_mul_f32 v[96:97], v[96:97], v[88:89]
	v_pk_mul_f32 v[98:99], v[98:99], v[90:91]
	v_pk_mul_f32 v[92:93], v[92:93], v[84:85]
	v_pk_mul_f32 v[94:95], v[94:95], v[86:87]
	v_or_b32_e32 v3, 0x20, v1
	v_cvt_pk_bf16_f32 v206, v96, v97
	v_cvt_pk_bf16_f32 v207, v98, v99
	v_cvt_pk_bf16_f32 v208, v92, v93
	v_cvt_pk_bf16_f32 v209, v94, v95
	v_mad_i64_i32 v[218:219], s[4:5], v3, s60, v[176:177]
	global_store_dwordx4 v[218:219], v[206:209], off
	v_pk_mul_f32 v[72:73], v[72:73], v[166:167] op_sel_hi:[1,0]
	v_pk_mul_f32 v[74:75], v[74:75], v[166:167] op_sel_hi:[1,0]
	v_pk_mul_f32 v[68:69], v[68:69], v[166:167] op_sel_hi:[1,0]
	v_pk_mul_f32 v[70:71], v[70:71], v[166:167] op_sel_hi:[1,0]
	v_pk_mul_f32 v[80:81], v[80:81], v[166:167] op_sel_hi:[1,0]
	v_pk_mul_f32 v[82:83], v[82:83], v[166:167] op_sel_hi:[1,0]
	v_pk_mul_f32 v[76:77], v[76:77], v[166:167] op_sel_hi:[1,0]
	v_pk_mul_f32 v[78:79], v[78:79], v[166:167] op_sel_hi:[1,0]
	v_pk_mul_f32 v[190:191], v[72:73], v[178:179] op_sel_hi:[1,0]
	v_pk_mul_f32 v[192:193], v[74:75], v[178:179] op_sel_hi:[1,0]
	v_pk_mul_f32 v[194:195], v[68:69], v[178:179] op_sel_hi:[1,0]
	v_pk_mul_f32 v[196:197], v[70:71], v[178:179] op_sel_hi:[1,0]
	v_exp_f32_e32 v190, v190
	v_exp_f32_e32 v191, v191
	v_exp_f32_e32 v192, v192
	v_exp_f32_e32 v193, v193
	v_exp_f32_e32 v194, v194
	v_exp_f32_e32 v195, v195
	v_exp_f32_e32 v196, v196
	v_exp_f32_e32 v197, v197
	v_pk_add_f32 v[190:191], v[190:191], v[180:181] op_sel_hi:[1,0]
	v_pk_add_f32 v[192:193], v[192:193], v[180:181] op_sel_hi:[1,0]
	v_pk_add_f32 v[194:195], v[194:195], v[180:181] op_sel_hi:[1,0]
	v_pk_add_f32 v[196:197], v[196:197], v[180:181] op_sel_hi:[1,0]
	v_rcp_f32_e32 v190, v190
	v_rcp_f32_e32 v191, v191
	v_rcp_f32_e32 v192, v192
	v_rcp_f32_e32 v193, v193
	v_rcp_f32_e32 v194, v194
	v_rcp_f32_e32 v195, v195
	v_rcp_f32_e32 v196, v196
	v_rcp_f32_e32 v197, v197
	v_pk_mul_f32 v[72:73], v[72:73], v[190:191]
	v_pk_mul_f32 v[74:75], v[74:75], v[192:193]
	v_pk_mul_f32 v[68:69], v[68:69], v[194:195]
	v_pk_mul_f32 v[70:71], v[70:71], v[196:197]
	v_pk_mul_f32 v[80:81], v[80:81], v[72:73]
	v_pk_mul_f32 v[82:83], v[82:83], v[74:75]
	v_pk_mul_f32 v[76:77], v[76:77], v[68:69]
	v_pk_mul_f32 v[78:79], v[78:79], v[70:71]
	v_or_b32_e32 v2, 0x30, v1
	v_cvt_pk_bf16_f32 v210, v80, v81
	v_cvt_pk_bf16_f32 v211, v82, v83
	v_cvt_pk_bf16_f32 v212, v76, v77
	v_cvt_pk_bf16_f32 v213, v78, v79
	v_mad_i64_i32 v[220:221], s[4:5], v2, s60, v[176:177]
	global_store_dwordx4 v[220:221], v[210:213], off
	v_pk_mul_f32 v[56:57], v[56:57], v[168:169] op_sel_hi:[1,0]
	v_pk_mul_f32 v[58:59], v[58:59], v[168:169] op_sel_hi:[1,0]
	v_pk_mul_f32 v[52:53], v[52:53], v[168:169] op_sel_hi:[1,0]
	v_pk_mul_f32 v[54:55], v[54:55], v[168:169] op_sel_hi:[1,0]
	v_pk_mul_f32 v[64:65], v[64:65], v[168:169] op_sel_hi:[1,0]
	v_pk_mul_f32 v[66:67], v[66:67], v[168:169] op_sel_hi:[1,0]
	v_pk_mul_f32 v[60:61], v[60:61], v[168:169] op_sel_hi:[1,0]
	v_pk_mul_f32 v[62:63], v[62:63], v[168:169] op_sel_hi:[1,0]
	v_pk_mul_f32 v[182:183], v[56:57], v[178:179] op_sel_hi:[1,0]
	v_pk_mul_f32 v[184:185], v[58:59], v[178:179] op_sel_hi:[1,0]
	v_pk_mul_f32 v[186:187], v[52:53], v[178:179] op_sel_hi:[1,0]
	v_pk_mul_f32 v[188:189], v[54:55], v[178:179] op_sel_hi:[1,0]
	v_exp_f32_e32 v182, v182
	v_exp_f32_e32 v183, v183
	v_exp_f32_e32 v184, v184
	v_exp_f32_e32 v185, v185
	v_exp_f32_e32 v186, v186
	v_exp_f32_e32 v187, v187
	v_exp_f32_e32 v188, v188
	v_exp_f32_e32 v189, v189
	v_pk_add_f32 v[182:183], v[182:183], v[180:181] op_sel_hi:[1,0]
	v_pk_add_f32 v[184:185], v[184:185], v[180:181] op_sel_hi:[1,0]
	v_pk_add_f32 v[186:187], v[186:187], v[180:181] op_sel_hi:[1,0]
	v_pk_add_f32 v[188:189], v[188:189], v[180:181] op_sel_hi:[1,0]
	v_rcp_f32_e32 v182, v182
	v_rcp_f32_e32 v183, v183
	v_rcp_f32_e32 v184, v184
	v_rcp_f32_e32 v185, v185
	v_rcp_f32_e32 v186, v186
	v_rcp_f32_e32 v187, v187
	v_rcp_f32_e32 v188, v188
	v_rcp_f32_e32 v189, v189
	v_pk_mul_f32 v[56:57], v[56:57], v[182:183]
	v_pk_mul_f32 v[58:59], v[58:59], v[184:185]
	v_pk_mul_f32 v[52:53], v[52:53], v[186:187]
	v_pk_mul_f32 v[54:55], v[54:55], v[188:189]
	v_pk_mul_f32 v[64:65], v[64:65], v[56:57]
	v_pk_mul_f32 v[66:67], v[66:67], v[58:59]
	v_pk_mul_f32 v[60:61], v[60:61], v[52:53]
	v_pk_mul_f32 v[62:63], v[62:63], v[54:55]
	v_add_u32_e32 v3, 0x80, v1
	v_cvt_pk_bf16_f32 v198, v64, v65
	v_cvt_pk_bf16_f32 v199, v66, v67
	v_cvt_pk_bf16_f32 v200, v60, v61
	v_cvt_pk_bf16_f32 v201, v62, v63
	v_mad_i64_i32 v[214:215], s[4:5], v3, s60, v[176:177]
	global_store_dwordx4 v[214:215], v[198:201], off
	v_pk_mul_f32 v[40:41], v[40:41], v[170:171] op_sel_hi:[1,0]
	v_pk_mul_f32 v[42:43], v[42:43], v[170:171] op_sel_hi:[1,0]
	v_pk_mul_f32 v[36:37], v[36:37], v[170:171] op_sel_hi:[1,0]
	v_pk_mul_f32 v[38:39], v[38:39], v[170:171] op_sel_hi:[1,0]
	v_pk_mul_f32 v[48:49], v[48:49], v[170:171] op_sel_hi:[1,0]
	v_pk_mul_f32 v[50:51], v[50:51], v[170:171] op_sel_hi:[1,0]
	v_pk_mul_f32 v[44:45], v[44:45], v[170:171] op_sel_hi:[1,0]
	v_pk_mul_f32 v[46:47], v[46:47], v[170:171] op_sel_hi:[1,0]
	v_pk_mul_f32 v[190:191], v[40:41], v[178:179] op_sel_hi:[1,0]
	v_pk_mul_f32 v[192:193], v[42:43], v[178:179] op_sel_hi:[1,0]
	v_pk_mul_f32 v[194:195], v[36:37], v[178:179] op_sel_hi:[1,0]
	v_pk_mul_f32 v[196:197], v[38:39], v[178:179] op_sel_hi:[1,0]
	v_exp_f32_e32 v190, v190
	v_exp_f32_e32 v191, v191
	v_exp_f32_e32 v192, v192
	v_exp_f32_e32 v193, v193
	v_exp_f32_e32 v194, v194
	v_exp_f32_e32 v195, v195
	v_exp_f32_e32 v196, v196
	v_exp_f32_e32 v197, v197
	v_pk_add_f32 v[190:191], v[190:191], v[180:181] op_sel_hi:[1,0]
	v_pk_add_f32 v[192:193], v[192:193], v[180:181] op_sel_hi:[1,0]
	v_pk_add_f32 v[194:195], v[194:195], v[180:181] op_sel_hi:[1,0]
	v_pk_add_f32 v[196:197], v[196:197], v[180:181] op_sel_hi:[1,0]
	v_rcp_f32_e32 v190, v190
	v_rcp_f32_e32 v191, v191
	v_rcp_f32_e32 v192, v192
	v_rcp_f32_e32 v193, v193
	v_rcp_f32_e32 v194, v194
	v_rcp_f32_e32 v195, v195
	v_rcp_f32_e32 v196, v196
	v_rcp_f32_e32 v197, v197
	v_pk_mul_f32 v[40:41], v[40:41], v[190:191]
	v_pk_mul_f32 v[42:43], v[42:43], v[192:193]
	v_pk_mul_f32 v[36:37], v[36:37], v[194:195]
	v_pk_mul_f32 v[38:39], v[38:39], v[196:197]
	v_pk_mul_f32 v[48:49], v[48:49], v[40:41]
	v_pk_mul_f32 v[50:51], v[50:51], v[42:43]
	v_pk_mul_f32 v[44:45], v[44:45], v[36:37]
	v_pk_mul_f32 v[46:47], v[46:47], v[38:39]
	v_add_u32_e32 v2, 0x90, v1
	v_cvt_pk_bf16_f32 v202, v48, v49
	v_cvt_pk_bf16_f32 v203, v50, v51
	v_cvt_pk_bf16_f32 v204, v44, v45
	v_cvt_pk_bf16_f32 v205, v46, v47
	v_mad_i64_i32 v[216:217], s[4:5], v2, s60, v[176:177]
	global_store_dwordx4 v[216:217], v[202:205], off
	v_pk_mul_f32 v[24:25], v[24:25], v[172:173] op_sel_hi:[1,0]
	v_pk_mul_f32 v[26:27], v[26:27], v[172:173] op_sel_hi:[1,0]
	v_pk_mul_f32 v[20:21], v[20:21], v[172:173] op_sel_hi:[1,0]
	v_pk_mul_f32 v[22:23], v[22:23], v[172:173] op_sel_hi:[1,0]
	v_pk_mul_f32 v[32:33], v[32:33], v[172:173] op_sel_hi:[1,0]
	v_pk_mul_f32 v[34:35], v[34:35], v[172:173] op_sel_hi:[1,0]
	v_pk_mul_f32 v[28:29], v[28:29], v[172:173] op_sel_hi:[1,0]
	v_pk_mul_f32 v[30:31], v[30:31], v[172:173] op_sel_hi:[1,0]
	v_pk_mul_f32 v[182:183], v[24:25], v[178:179] op_sel_hi:[1,0]
	v_pk_mul_f32 v[184:185], v[26:27], v[178:179] op_sel_hi:[1,0]
	v_pk_mul_f32 v[186:187], v[20:21], v[178:179] op_sel_hi:[1,0]
	v_pk_mul_f32 v[188:189], v[22:23], v[178:179] op_sel_hi:[1,0]
	v_exp_f32_e32 v182, v182
	v_exp_f32_e32 v183, v183
	v_exp_f32_e32 v184, v184
	v_exp_f32_e32 v185, v185
	v_exp_f32_e32 v186, v186
	v_exp_f32_e32 v187, v187
	v_exp_f32_e32 v188, v188
	v_exp_f32_e32 v189, v189
	v_pk_add_f32 v[182:183], v[182:183], v[180:181] op_sel_hi:[1,0]
	v_pk_add_f32 v[184:185], v[184:185], v[180:181] op_sel_hi:[1,0]
	v_pk_add_f32 v[186:187], v[186:187], v[180:181] op_sel_hi:[1,0]
	v_pk_add_f32 v[188:189], v[188:189], v[180:181] op_sel_hi:[1,0]
	v_rcp_f32_e32 v182, v182
	v_rcp_f32_e32 v183, v183
	v_rcp_f32_e32 v184, v184
	v_rcp_f32_e32 v185, v185
	v_rcp_f32_e32 v186, v186
	v_rcp_f32_e32 v187, v187
	v_rcp_f32_e32 v188, v188
	v_rcp_f32_e32 v189, v189
	v_pk_mul_f32 v[24:25], v[24:25], v[182:183]
	v_pk_mul_f32 v[26:27], v[26:27], v[184:185]
	v_pk_mul_f32 v[20:21], v[20:21], v[186:187]
	v_pk_mul_f32 v[22:23], v[22:23], v[188:189]
	v_pk_mul_f32 v[32:33], v[32:33], v[24:25]
	v_pk_mul_f32 v[34:35], v[34:35], v[26:27]
	v_pk_mul_f32 v[28:29], v[28:29], v[20:21]
	v_pk_mul_f32 v[30:31], v[30:31], v[22:23]
	v_add_u32_e32 v3, 0xa0, v1
	v_cvt_pk_bf16_f32 v206, v32, v33
	v_cvt_pk_bf16_f32 v207, v34, v35
	v_cvt_pk_bf16_f32 v208, v28, v29
	v_cvt_pk_bf16_f32 v209, v30, v31
	v_mad_i64_i32 v[218:219], s[0:1], v3, s60, v[176:177]
	global_store_dwordx4 v[218:219], v[206:209], off
	v_pk_mul_f32 v[8:9], v[8:9], v[174:175] op_sel_hi:[1,0]
	v_pk_mul_f32 v[10:11], v[10:11], v[174:175] op_sel_hi:[1,0]
	v_pk_mul_f32 v[4:5], v[4:5], v[174:175] op_sel_hi:[1,0]
	v_pk_mul_f32 v[6:7], v[6:7], v[174:175] op_sel_hi:[1,0]
	v_pk_mul_f32 v[16:17], v[16:17], v[174:175] op_sel_hi:[1,0]
	v_pk_mul_f32 v[18:19], v[18:19], v[174:175] op_sel_hi:[1,0]
	v_pk_mul_f32 v[12:13], v[12:13], v[174:175] op_sel_hi:[1,0]
	v_pk_mul_f32 v[14:15], v[14:15], v[174:175] op_sel_hi:[1,0]
	v_pk_mul_f32 v[190:191], v[8:9], v[178:179] op_sel_hi:[1,0]
	v_pk_mul_f32 v[192:193], v[10:11], v[178:179] op_sel_hi:[1,0]
	v_pk_mul_f32 v[194:195], v[4:5], v[178:179] op_sel_hi:[1,0]
	v_pk_mul_f32 v[196:197], v[6:7], v[178:179] op_sel_hi:[1,0]
	v_exp_f32_e32 v190, v190
	v_exp_f32_e32 v191, v191
	v_exp_f32_e32 v192, v192
	v_exp_f32_e32 v193, v193
	v_exp_f32_e32 v194, v194
	v_exp_f32_e32 v195, v195
	v_exp_f32_e32 v196, v196
	v_exp_f32_e32 v197, v197
	v_pk_add_f32 v[190:191], v[190:191], v[180:181] op_sel_hi:[1,0]
	v_pk_add_f32 v[192:193], v[192:193], v[180:181] op_sel_hi:[1,0]
	v_pk_add_f32 v[194:195], v[194:195], v[180:181] op_sel_hi:[1,0]
	v_pk_add_f32 v[196:197], v[196:197], v[180:181] op_sel_hi:[1,0]
	v_rcp_f32_e32 v190, v190
	v_rcp_f32_e32 v191, v191
	v_rcp_f32_e32 v192, v192
	v_rcp_f32_e32 v193, v193
	v_rcp_f32_e32 v194, v194
	v_rcp_f32_e32 v195, v195
	v_rcp_f32_e32 v196, v196
	v_rcp_f32_e32 v197, v197
	v_pk_mul_f32 v[8:9], v[8:9], v[190:191]
	v_pk_mul_f32 v[10:11], v[10:11], v[192:193]
	v_pk_mul_f32 v[4:5], v[4:5], v[194:195]
	v_pk_mul_f32 v[6:7], v[6:7], v[196:197]
	v_pk_mul_f32 v[16:17], v[16:17], v[8:9]
	v_pk_mul_f32 v[18:19], v[18:19], v[10:11]
	v_pk_mul_f32 v[12:13], v[12:13], v[4:5]
	v_pk_mul_f32 v[14:15], v[14:15], v[6:7]
	v_add_u32_e32 v2, 0xb0, v1
	v_cvt_pk_bf16_f32 v210, v16, v17
	v_cvt_pk_bf16_f32 v211, v18, v19
	v_cvt_pk_bf16_f32 v212, v12, v13
	v_cvt_pk_bf16_f32 v213, v14, v15
	v_mad_i64_i32 v[220:221], s[0:1], v2, s60, v[176:177]
	s_nop 0
	s_mov_b64 s[0:1], -1
	global_store_dwordx4 v[220:221], v[210:213], off
	s_cbranch_vccnz .LBB0_661
	s_andn2_b64 vcc, exec, s[26:27]
	s_cbranch_vccnz .LBB0_660
	s_barrier
	s_branch .LBB0_660

.LBB0_806:
	s_waitcnt lgkmcnt(0)
	s_lshl_b32 s0, s67, 10
	s_and_b32 s0, s0, 0x400
	s_add_i32 s0, s0, 0x20000
	s_and_b64 vcc, exec, s[8:9]
	v_lshl_add_u32 v1, s52, 8, v151
	v_lshl_add_u32 v2, v154, 2, s0
	ds_read_b32 v160, v2
	v_bitop3_b32 v3, v1, s63, 16 bitop3:0xc8
	v_lshl_add_u32 v3, v3, 2, s0
	ds_read_b32 v162, v3
	v_bitop3_b32 v2, v1, s64, 32 bitop3:0xc8
	v_lshl_add_u32 v2, v2, 2, s0
	ds_read_b32 v164, v2
	v_bitop3_b32 v3, v1, s65, 48 bitop3:0xc8
	v_lshl_add_u32 v3, v3, 2, s0
	ds_read_b32 v166, v3
	v_add_u32_e32 v2, 0x80, v1
	v_and_b32_e32 v2, 0xcf, v2
	v_lshl_add_u32 v2, v2, 2, s0
	ds_read_b32 v168, v2
	v_add_u32_e32 v3, 0x90, v1
	v_and_b32_e32 v3, 0xdf, v3
	v_lshl_add_u32 v3, v3, 2, s0
	ds_read_b32 v170, v3
	v_add_u32_e32 v2, 0xa0, v1
	v_and_b32_e32 v2, 0xef, v2
	v_lshl_add_u32 v2, v2, 2, s0
	ds_read_b32 v172, v2
	v_add_u32_e32 v3, 0xb0, v1
	v_and_b32_e32 v3, 0xff, v3
	v_lshl_add_u32 v3, v3, 2, s0
	ds_read_b32 v174, v3
	v_lshl_add_u32 v158, s54, 7, v153
	v_ashrrev_i32_e32 v159, 31, v158
	v_mov_b64_e32 v[176:177], s[28:29]
	v_mov_b32_e32 v178, 0xbfb8aa3b
	v_mov_b32_e32 v180, 1.0
	v_lshl_add_u64 v[176:177], v[158:159], 1, v[176:177]
	s_waitcnt lgkmcnt(0)
	v_pk_mul_f32 v[120:121], v[120:121], v[160:161] op_sel_hi:[1,0]
	v_pk_mul_f32 v[122:123], v[122:123], v[160:161] op_sel_hi:[1,0]
	v_pk_mul_f32 v[116:117], v[116:117], v[160:161] op_sel_hi:[1,0]
	v_pk_mul_f32 v[118:119], v[118:119], v[160:161] op_sel_hi:[1,0]
	v_pk_mul_f32 v[128:129], v[128:129], v[160:161] op_sel_hi:[1,0]
	v_pk_mul_f32 v[130:131], v[130:131], v[160:161] op_sel_hi:[1,0]
	v_pk_mul_f32 v[124:125], v[124:125], v[160:161] op_sel_hi:[1,0]
	v_pk_mul_f32 v[126:127], v[126:127], v[160:161] op_sel_hi:[1,0]
	v_pk_mul_f32 v[182:183], v[120:121], v[178:179] op_sel_hi:[1,0]
	v_pk_mul_f32 v[184:185], v[122:123], v[178:179] op_sel_hi:[1,0]
	v_pk_mul_f32 v[186:187], v[116:117], v[178:179] op_sel_hi:[1,0]
	v_pk_mul_f32 v[188:189], v[118:119], v[178:179] op_sel_hi:[1,0]
	v_exp_f32_e32 v182, v182
	v_exp_f32_e32 v183, v183
	v_exp_f32_e32 v184, v184
	v_exp_f32_e32 v185, v185
	v_exp_f32_e32 v186, v186
	v_exp_f32_e32 v187, v187
	v_exp_f32_e32 v188, v188
	v_exp_f32_e32 v189, v189
	v_pk_add_f32 v[182:183], v[182:183], v[180:181] op_sel_hi:[1,0]
	v_pk_add_f32 v[184:185], v[184:185], v[180:181] op_sel_hi:[1,0]
	v_pk_add_f32 v[186:187], v[186:187], v[180:181] op_sel_hi:[1,0]
	v_pk_add_f32 v[188:189], v[188:189], v[180:181] op_sel_hi:[1,0]
	v_rcp_f32_e32 v182, v182
	v_rcp_f32_e32 v183, v183
	v_rcp_f32_e32 v184, v184
	v_rcp_f32_e32 v185, v185
	v_rcp_f32_e32 v186, v186
	v_rcp_f32_e32 v187, v187
	v_rcp_f32_e32 v188, v188
	v_rcp_f32_e32 v189, v189
	v_pk_mul_f32 v[120:121], v[120:121], v[182:183]
	v_pk_mul_f32 v[122:123], v[122:123], v[184:185]
	v_pk_mul_f32 v[116:117], v[116:117], v[186:187]
	v_pk_mul_f32 v[118:119], v[118:119], v[188:189]
	v_pk_mul_f32 v[128:129], v[128:129], v[120:121]
	v_pk_mul_f32 v[130:131], v[130:131], v[122:123]
	v_pk_mul_f32 v[124:125], v[124:125], v[116:117]
	v_pk_mul_f32 v[126:127], v[126:127], v[118:119]
	v_cvt_pk_bf16_f32 v198, v128, v129
	v_cvt_pk_bf16_f32 v199, v130, v131
	v_cvt_pk_bf16_f32 v200, v124, v125
	v_cvt_pk_bf16_f32 v201, v126, v127
	v_mad_i64_i32 v[214:215], s[6:7], v1, s62, v[176:177]
	global_store_dwordx4 v[214:215], v[198:201], off
	v_pk_mul_f32 v[104:105], v[104:105], v[162:163] op_sel_hi:[1,0]
	v_pk_mul_f32 v[106:107], v[106:107], v[162:163] op_sel_hi:[1,0]
	v_pk_mul_f32 v[100:101], v[100:101], v[162:163] op_sel_hi:[1,0]
	v_pk_mul_f32 v[102:103], v[102:103], v[162:163] op_sel_hi:[1,0]
	v_pk_mul_f32 v[112:113], v[112:113], v[162:163] op_sel_hi:[1,0]
	v_pk_mul_f32 v[114:115], v[114:115], v[162:163] op_sel_hi:[1,0]
	v_pk_mul_f32 v[108:109], v[108:109], v[162:163] op_sel_hi:[1,0]
	v_pk_mul_f32 v[110:111], v[110:111], v[162:163] op_sel_hi:[1,0]
	v_pk_mul_f32 v[190:191], v[104:105], v[178:179] op_sel_hi:[1,0]
	v_pk_mul_f32 v[192:193], v[106:107], v[178:179] op_sel_hi:[1,0]
	v_pk_mul_f32 v[194:195], v[100:101], v[178:179] op_sel_hi:[1,0]
	v_pk_mul_f32 v[196:197], v[102:103], v[178:179] op_sel_hi:[1,0]
	v_exp_f32_e32 v190, v190
	v_exp_f32_e32 v191, v191
	v_exp_f32_e32 v192, v192
	v_exp_f32_e32 v193, v193
	v_exp_f32_e32 v194, v194
	v_exp_f32_e32 v195, v195
	v_exp_f32_e32 v196, v196
	v_exp_f32_e32 v197, v197
	v_pk_add_f32 v[190:191], v[190:191], v[180:181] op_sel_hi:[1,0]
	v_pk_add_f32 v[192:193], v[192:193], v[180:181] op_sel_hi:[1,0]
	v_pk_add_f32 v[194:195], v[194:195], v[180:181] op_sel_hi:[1,0]
	v_pk_add_f32 v[196:197], v[196:197], v[180:181] op_sel_hi:[1,0]
	v_rcp_f32_e32 v190, v190
	v_rcp_f32_e32 v191, v191
	v_rcp_f32_e32 v192, v192
	v_rcp_f32_e32 v193, v193
	v_rcp_f32_e32 v194, v194
	v_rcp_f32_e32 v195, v195
	v_rcp_f32_e32 v196, v196
	v_rcp_f32_e32 v197, v197
	v_pk_mul_f32 v[104:105], v[104:105], v[190:191]
	v_pk_mul_f32 v[106:107], v[106:107], v[192:193]
	v_pk_mul_f32 v[100:101], v[100:101], v[194:195]
	v_pk_mul_f32 v[102:103], v[102:103], v[196:197]
	v_pk_mul_f32 v[112:113], v[112:113], v[104:105]
	v_pk_mul_f32 v[114:115], v[114:115], v[106:107]
	v_pk_mul_f32 v[108:109], v[108:109], v[100:101]
	v_pk_mul_f32 v[110:111], v[110:111], v[102:103]
	v_or_b32_e32 v2, 0x10, v1
	v_cvt_pk_bf16_f32 v202, v112, v113
	v_cvt_pk_bf16_f32 v203, v114, v115
	v_cvt_pk_bf16_f32 v204, v108, v109
	v_cvt_pk_bf16_f32 v205, v110, v111
	v_mad_i64_i32 v[216:217], s[6:7], v2, s62, v[176:177]
	global_store_dwordx4 v[216:217], v[202:205], off
	v_pk_mul_f32 v[88:89], v[88:89], v[164:165] op_sel_hi:[1,0]
	v_pk_mul_f32 v[90:91], v[90:91], v[164:165] op_sel_hi:[1,0]
	v_pk_mul_f32 v[84:85], v[84:85], v[164:165] op_sel_hi:[1,0]
	v_pk_mul_f32 v[86:87], v[86:87], v[164:165] op_sel_hi:[1,0]
	v_pk_mul_f32 v[96:97], v[96:97], v[164:165] op_sel_hi:[1,0]
	v_pk_mul_f32 v[98:99], v[98:99], v[164:165] op_sel_hi:[1,0]
	v_pk_mul_f32 v[92:93], v[92:93], v[164:165] op_sel_hi:[1,0]
	v_pk_mul_f32 v[94:95], v[94:95], v[164:165] op_sel_hi:[1,0]
	v_pk_mul_f32 v[182:183], v[88:89], v[178:179] op_sel_hi:[1,0]
	v_pk_mul_f32 v[184:185], v[90:91], v[178:179] op_sel_hi:[1,0]
	v_pk_mul_f32 v[186:187], v[84:85], v[178:179] op_sel_hi:[1,0]
	v_pk_mul_f32 v[188:189], v[86:87], v[178:179] op_sel_hi:[1,0]
	v_exp_f32_e32 v182, v182
	v_exp_f32_e32 v183, v183
	v_exp_f32_e32 v184, v184
	v_exp_f32_e32 v185, v185
	v_exp_f32_e32 v186, v186
	v_exp_f32_e32 v187, v187
	v_exp_f32_e32 v188, v188
	v_exp_f32_e32 v189, v189
	v_pk_add_f32 v[182:183], v[182:183], v[180:181] op_sel_hi:[1,0]
	v_pk_add_f32 v[184:185], v[184:185], v[180:181] op_sel_hi:[1,0]
	v_pk_add_f32 v[186:187], v[186:187], v[180:181] op_sel_hi:[1,0]
	v_pk_add_f32 v[188:189], v[188:189], v[180:181] op_sel_hi:[1,0]
	v_rcp_f32_e32 v182, v182
	v_rcp_f32_e32 v183, v183
	v_rcp_f32_e32 v184, v184
	v_rcp_f32_e32 v185, v185
	v_rcp_f32_e32 v186, v186
	v_rcp_f32_e32 v187, v187
	v_rcp_f32_e32 v188, v188
	v_rcp_f32_e32 v189, v189
	v_pk_mul_f32 v[88:89], v[88:89], v[182:183]
	v_pk_mul_f32 v[90:91], v[90:91], v[184:185]
	v_pk_mul_f32 v[84:85], v[84:85], v[186:187]
	v_pk_mul_f32 v[86:87], v[86:87], v[188:189]
	v_pk_mul_f32 v[96:97], v[96:97], v[88:89]
	v_pk_mul_f32 v[98:99], v[98:99], v[90:91]
	v_pk_mul_f32 v[92:93], v[92:93], v[84:85]
	v_pk_mul_f32 v[94:95], v[94:95], v[86:87]
	v_or_b32_e32 v3, 0x20, v1
	v_cvt_pk_bf16_f32 v206, v96, v97
	v_cvt_pk_bf16_f32 v207, v98, v99
	v_cvt_pk_bf16_f32 v208, v92, v93
	v_cvt_pk_bf16_f32 v209, v94, v95
	v_mad_i64_i32 v[218:219], s[6:7], v3, s62, v[176:177]
	global_store_dwordx4 v[218:219], v[206:209], off
	v_pk_mul_f32 v[72:73], v[72:73], v[166:167] op_sel_hi:[1,0]
	v_pk_mul_f32 v[74:75], v[74:75], v[166:167] op_sel_hi:[1,0]
	v_pk_mul_f32 v[68:69], v[68:69], v[166:167] op_sel_hi:[1,0]
	v_pk_mul_f32 v[70:71], v[70:71], v[166:167] op_sel_hi:[1,0]
	v_pk_mul_f32 v[80:81], v[80:81], v[166:167] op_sel_hi:[1,0]
	v_pk_mul_f32 v[82:83], v[82:83], v[166:167] op_sel_hi:[1,0]
	v_pk_mul_f32 v[76:77], v[76:77], v[166:167] op_sel_hi:[1,0]
	v_pk_mul_f32 v[78:79], v[78:79], v[166:167] op_sel_hi:[1,0]
	v_pk_mul_f32 v[190:191], v[72:73], v[178:179] op_sel_hi:[1,0]
	v_pk_mul_f32 v[192:193], v[74:75], v[178:179] op_sel_hi:[1,0]
	v_pk_mul_f32 v[194:195], v[68:69], v[178:179] op_sel_hi:[1,0]
	v_pk_mul_f32 v[196:197], v[70:71], v[178:179] op_sel_hi:[1,0]
	v_exp_f32_e32 v190, v190
	v_exp_f32_e32 v191, v191
	v_exp_f32_e32 v192, v192
	v_exp_f32_e32 v193, v193
	v_exp_f32_e32 v194, v194
	v_exp_f32_e32 v195, v195
	v_exp_f32_e32 v196, v196
	v_exp_f32_e32 v197, v197
	v_pk_add_f32 v[190:191], v[190:191], v[180:181] op_sel_hi:[1,0]
	v_pk_add_f32 v[192:193], v[192:193], v[180:181] op_sel_hi:[1,0]
	v_pk_add_f32 v[194:195], v[194:195], v[180:181] op_sel_hi:[1,0]
	v_pk_add_f32 v[196:197], v[196:197], v[180:181] op_sel_hi:[1,0]
	v_rcp_f32_e32 v190, v190
	v_rcp_f32_e32 v191, v191
	v_rcp_f32_e32 v192, v192
	v_rcp_f32_e32 v193, v193
	v_rcp_f32_e32 v194, v194
	v_rcp_f32_e32 v195, v195
	v_rcp_f32_e32 v196, v196
	v_rcp_f32_e32 v197, v197
	v_pk_mul_f32 v[72:73], v[72:73], v[190:191]
	v_pk_mul_f32 v[74:75], v[74:75], v[192:193]
	v_pk_mul_f32 v[68:69], v[68:69], v[194:195]
	v_pk_mul_f32 v[70:71], v[70:71], v[196:197]
	v_pk_mul_f32 v[80:81], v[80:81], v[72:73]
	v_pk_mul_f32 v[82:83], v[82:83], v[74:75]
	v_pk_mul_f32 v[76:77], v[76:77], v[68:69]
	v_pk_mul_f32 v[78:79], v[78:79], v[70:71]
	v_or_b32_e32 v2, 0x30, v1
	v_cvt_pk_bf16_f32 v210, v80, v81
	v_cvt_pk_bf16_f32 v211, v82, v83
	v_cvt_pk_bf16_f32 v212, v76, v77
	v_cvt_pk_bf16_f32 v213, v78, v79
	v_mad_i64_i32 v[220:221], s[6:7], v2, s62, v[176:177]
	global_store_dwordx4 v[220:221], v[210:213], off
	v_pk_mul_f32 v[56:57], v[56:57], v[168:169] op_sel_hi:[1,0]
	v_pk_mul_f32 v[58:59], v[58:59], v[168:169] op_sel_hi:[1,0]
	v_pk_mul_f32 v[52:53], v[52:53], v[168:169] op_sel_hi:[1,0]
	v_pk_mul_f32 v[54:55], v[54:55], v[168:169] op_sel_hi:[1,0]
	v_pk_mul_f32 v[64:65], v[64:65], v[168:169] op_sel_hi:[1,0]
	v_pk_mul_f32 v[66:67], v[66:67], v[168:169] op_sel_hi:[1,0]
	v_pk_mul_f32 v[60:61], v[60:61], v[168:169] op_sel_hi:[1,0]
	v_pk_mul_f32 v[62:63], v[62:63], v[168:169] op_sel_hi:[1,0]
	v_pk_mul_f32 v[182:183], v[56:57], v[178:179] op_sel_hi:[1,0]
	v_pk_mul_f32 v[184:185], v[58:59], v[178:179] op_sel_hi:[1,0]
	v_pk_mul_f32 v[186:187], v[52:53], v[178:179] op_sel_hi:[1,0]
	v_pk_mul_f32 v[188:189], v[54:55], v[178:179] op_sel_hi:[1,0]
	v_exp_f32_e32 v182, v182
	v_exp_f32_e32 v183, v183
	v_exp_f32_e32 v184, v184
	v_exp_f32_e32 v185, v185
	v_exp_f32_e32 v186, v186
	v_exp_f32_e32 v187, v187
	v_exp_f32_e32 v188, v188
	v_exp_f32_e32 v189, v189
	v_pk_add_f32 v[182:183], v[182:183], v[180:181] op_sel_hi:[1,0]
	v_pk_add_f32 v[184:185], v[184:185], v[180:181] op_sel_hi:[1,0]
	v_pk_add_f32 v[186:187], v[186:187], v[180:181] op_sel_hi:[1,0]
	v_pk_add_f32 v[188:189], v[188:189], v[180:181] op_sel_hi:[1,0]
	v_rcp_f32_e32 v182, v182
	v_rcp_f32_e32 v183, v183
	v_rcp_f32_e32 v184, v184
	v_rcp_f32_e32 v185, v185
	v_rcp_f32_e32 v186, v186
	v_rcp_f32_e32 v187, v187
	v_rcp_f32_e32 v188, v188
	v_rcp_f32_e32 v189, v189
	v_pk_mul_f32 v[56:57], v[56:57], v[182:183]
	v_pk_mul_f32 v[58:59], v[58:59], v[184:185]
	v_pk_mul_f32 v[52:53], v[52:53], v[186:187]
	v_pk_mul_f32 v[54:55], v[54:55], v[188:189]
	v_pk_mul_f32 v[64:65], v[64:65], v[56:57]
	v_pk_mul_f32 v[66:67], v[66:67], v[58:59]
	v_pk_mul_f32 v[60:61], v[60:61], v[52:53]
	v_pk_mul_f32 v[62:63], v[62:63], v[54:55]
	v_add_u32_e32 v3, 0x80, v1
	v_cvt_pk_bf16_f32 v198, v64, v65
	v_cvt_pk_bf16_f32 v199, v66, v67
	v_cvt_pk_bf16_f32 v200, v60, v61
	v_cvt_pk_bf16_f32 v201, v62, v63
	v_mad_i64_i32 v[214:215], s[6:7], v3, s62, v[176:177]
	global_store_dwordx4 v[214:215], v[198:201], off
	v_pk_mul_f32 v[40:41], v[40:41], v[170:171] op_sel_hi:[1,0]
	v_pk_mul_f32 v[42:43], v[42:43], v[170:171] op_sel_hi:[1,0]
	v_pk_mul_f32 v[36:37], v[36:37], v[170:171] op_sel_hi:[1,0]
	v_pk_mul_f32 v[38:39], v[38:39], v[170:171] op_sel_hi:[1,0]
	v_pk_mul_f32 v[48:49], v[48:49], v[170:171] op_sel_hi:[1,0]
	v_pk_mul_f32 v[50:51], v[50:51], v[170:171] op_sel_hi:[1,0]
	v_pk_mul_f32 v[44:45], v[44:45], v[170:171] op_sel_hi:[1,0]
	v_pk_mul_f32 v[46:47], v[46:47], v[170:171] op_sel_hi:[1,0]
	v_pk_mul_f32 v[190:191], v[40:41], v[178:179] op_sel_hi:[1,0]
	v_pk_mul_f32 v[192:193], v[42:43], v[178:179] op_sel_hi:[1,0]
	v_pk_mul_f32 v[194:195], v[36:37], v[178:179] op_sel_hi:[1,0]
	v_pk_mul_f32 v[196:197], v[38:39], v[178:179] op_sel_hi:[1,0]
	v_exp_f32_e32 v190, v190
	v_exp_f32_e32 v191, v191
	v_exp_f32_e32 v192, v192
	v_exp_f32_e32 v193, v193
	v_exp_f32_e32 v194, v194
	v_exp_f32_e32 v195, v195
	v_exp_f32_e32 v196, v196
	v_exp_f32_e32 v197, v197
	v_pk_add_f32 v[190:191], v[190:191], v[180:181] op_sel_hi:[1,0]
	v_pk_add_f32 v[192:193], v[192:193], v[180:181] op_sel_hi:[1,0]
	v_pk_add_f32 v[194:195], v[194:195], v[180:181] op_sel_hi:[1,0]
	v_pk_add_f32 v[196:197], v[196:197], v[180:181] op_sel_hi:[1,0]
	v_rcp_f32_e32 v190, v190
	v_rcp_f32_e32 v191, v191
	v_rcp_f32_e32 v192, v192
	v_rcp_f32_e32 v193, v193
	v_rcp_f32_e32 v194, v194
	v_rcp_f32_e32 v195, v195
	v_rcp_f32_e32 v196, v196
	v_rcp_f32_e32 v197, v197
	v_pk_mul_f32 v[40:41], v[40:41], v[190:191]
	v_pk_mul_f32 v[42:43], v[42:43], v[192:193]
	v_pk_mul_f32 v[36:37], v[36:37], v[194:195]
	v_pk_mul_f32 v[38:39], v[38:39], v[196:197]
	v_pk_mul_f32 v[48:49], v[48:49], v[40:41]
	v_pk_mul_f32 v[50:51], v[50:51], v[42:43]
	v_pk_mul_f32 v[44:45], v[44:45], v[36:37]
	v_pk_mul_f32 v[46:47], v[46:47], v[38:39]
	v_add_u32_e32 v2, 0x90, v1
	v_cvt_pk_bf16_f32 v202, v48, v49
	v_cvt_pk_bf16_f32 v203, v50, v51
	v_cvt_pk_bf16_f32 v204, v44, v45
	v_cvt_pk_bf16_f32 v205, v46, v47
	v_mad_i64_i32 v[216:217], s[6:7], v2, s62, v[176:177]
	global_store_dwordx4 v[216:217], v[202:205], off
	v_pk_mul_f32 v[24:25], v[24:25], v[172:173] op_sel_hi:[1,0]
	v_pk_mul_f32 v[26:27], v[26:27], v[172:173] op_sel_hi:[1,0]
	v_pk_mul_f32 v[20:21], v[20:21], v[172:173] op_sel_hi:[1,0]
	v_pk_mul_f32 v[22:23], v[22:23], v[172:173] op_sel_hi:[1,0]
	v_pk_mul_f32 v[32:33], v[32:33], v[172:173] op_sel_hi:[1,0]
	v_pk_mul_f32 v[34:35], v[34:35], v[172:173] op_sel_hi:[1,0]
	v_pk_mul_f32 v[28:29], v[28:29], v[172:173] op_sel_hi:[1,0]
	v_pk_mul_f32 v[30:31], v[30:31], v[172:173] op_sel_hi:[1,0]
	v_pk_mul_f32 v[182:183], v[24:25], v[178:179] op_sel_hi:[1,0]
	v_pk_mul_f32 v[184:185], v[26:27], v[178:179] op_sel_hi:[1,0]
	v_pk_mul_f32 v[186:187], v[20:21], v[178:179] op_sel_hi:[1,0]
	v_pk_mul_f32 v[188:189], v[22:23], v[178:179] op_sel_hi:[1,0]
	v_exp_f32_e32 v182, v182
	v_exp_f32_e32 v183, v183
	v_exp_f32_e32 v184, v184
	v_exp_f32_e32 v185, v185
	v_exp_f32_e32 v186, v186
	v_exp_f32_e32 v187, v187
	v_exp_f32_e32 v188, v188
	v_exp_f32_e32 v189, v189
	v_pk_add_f32 v[182:183], v[182:183], v[180:181] op_sel_hi:[1,0]
	v_pk_add_f32 v[184:185], v[184:185], v[180:181] op_sel_hi:[1,0]
	v_pk_add_f32 v[186:187], v[186:187], v[180:181] op_sel_hi:[1,0]
	v_pk_add_f32 v[188:189], v[188:189], v[180:181] op_sel_hi:[1,0]
	v_rcp_f32_e32 v182, v182
	v_rcp_f32_e32 v183, v183
	v_rcp_f32_e32 v184, v184
	v_rcp_f32_e32 v185, v185
	v_rcp_f32_e32 v186, v186
	v_rcp_f32_e32 v187, v187
	v_rcp_f32_e32 v188, v188
	v_rcp_f32_e32 v189, v189
	v_pk_mul_f32 v[24:25], v[24:25], v[182:183]
	v_pk_mul_f32 v[26:27], v[26:27], v[184:185]
	v_pk_mul_f32 v[20:21], v[20:21], v[186:187]
	v_pk_mul_f32 v[22:23], v[22:23], v[188:189]
	v_pk_mul_f32 v[32:33], v[32:33], v[24:25]
	v_pk_mul_f32 v[34:35], v[34:35], v[26:27]
	v_pk_mul_f32 v[28:29], v[28:29], v[20:21]
	v_pk_mul_f32 v[30:31], v[30:31], v[22:23]
	v_add_u32_e32 v3, 0xa0, v1
	v_cvt_pk_bf16_f32 v206, v32, v33
	v_cvt_pk_bf16_f32 v207, v34, v35
	v_cvt_pk_bf16_f32 v208, v28, v29
	v_cvt_pk_bf16_f32 v209, v30, v31
	v_mad_i64_i32 v[218:219], s[0:1], v3, s62, v[176:177]
	global_store_dwordx4 v[218:219], v[206:209], off
	v_pk_mul_f32 v[8:9], v[8:9], v[174:175] op_sel_hi:[1,0]
	v_pk_mul_f32 v[10:11], v[10:11], v[174:175] op_sel_hi:[1,0]
	v_pk_mul_f32 v[4:5], v[4:5], v[174:175] op_sel_hi:[1,0]
	v_pk_mul_f32 v[6:7], v[6:7], v[174:175] op_sel_hi:[1,0]
	v_pk_mul_f32 v[16:17], v[16:17], v[174:175] op_sel_hi:[1,0]
	v_pk_mul_f32 v[18:19], v[18:19], v[174:175] op_sel_hi:[1,0]
	v_pk_mul_f32 v[12:13], v[12:13], v[174:175] op_sel_hi:[1,0]
	v_pk_mul_f32 v[14:15], v[14:15], v[174:175] op_sel_hi:[1,0]
	v_pk_mul_f32 v[190:191], v[8:9], v[178:179] op_sel_hi:[1,0]
	v_pk_mul_f32 v[192:193], v[10:11], v[178:179] op_sel_hi:[1,0]
	v_pk_mul_f32 v[194:195], v[4:5], v[178:179] op_sel_hi:[1,0]
	v_pk_mul_f32 v[196:197], v[6:7], v[178:179] op_sel_hi:[1,0]
	v_exp_f32_e32 v190, v190
	v_exp_f32_e32 v191, v191
	v_exp_f32_e32 v192, v192
	v_exp_f32_e32 v193, v193
	v_exp_f32_e32 v194, v194
	v_exp_f32_e32 v195, v195
	v_exp_f32_e32 v196, v196
	v_exp_f32_e32 v197, v197
	v_pk_add_f32 v[190:191], v[190:191], v[180:181] op_sel_hi:[1,0]
	v_pk_add_f32 v[192:193], v[192:193], v[180:181] op_sel_hi:[1,0]
	v_pk_add_f32 v[194:195], v[194:195], v[180:181] op_sel_hi:[1,0]
	v_pk_add_f32 v[196:197], v[196:197], v[180:181] op_sel_hi:[1,0]
	v_rcp_f32_e32 v190, v190
	v_rcp_f32_e32 v191, v191
	v_rcp_f32_e32 v192, v192
	v_rcp_f32_e32 v193, v193
	v_rcp_f32_e32 v194, v194
	v_rcp_f32_e32 v195, v195
	v_rcp_f32_e32 v196, v196
	v_rcp_f32_e32 v197, v197
	v_pk_mul_f32 v[8:9], v[8:9], v[190:191]
	v_pk_mul_f32 v[10:11], v[10:11], v[192:193]
	v_pk_mul_f32 v[4:5], v[4:5], v[194:195]
	v_pk_mul_f32 v[6:7], v[6:7], v[196:197]
	v_pk_mul_f32 v[16:17], v[16:17], v[8:9]
	v_pk_mul_f32 v[18:19], v[18:19], v[10:11]
	v_pk_mul_f32 v[12:13], v[12:13], v[4:5]
	v_pk_mul_f32 v[14:15], v[14:15], v[6:7]
	v_add_u32_e32 v2, 0xb0, v1
	v_cvt_pk_bf16_f32 v210, v16, v17
	v_cvt_pk_bf16_f32 v211, v18, v19
	v_cvt_pk_bf16_f32 v212, v12, v13
	v_cvt_pk_bf16_f32 v213, v14, v15
	v_mad_i64_i32 v[220:221], s[0:1], v2, s62, v[176:177]
	s_nop 0
	s_mov_b64 s[0:1], -1
	global_store_dwordx4 v[220:221], v[210:213], off
	s_cbranch_vccnz .LBB0_794
	s_andn2_b64 vcc, exec, s[30:31]
	s_cbranch_vccnz .LBB0_793
	s_barrier
	s_branch .LBB0_793
